# layer-1 weight conversion items (11776 of 48128) moved from phase 0 to the workgroups idle in the in-projection's quarter-full last round (possible now that the conditioning GEMV there is pipelined)
# speedup vs baseline: 1.0032x; 1.0032x over previous
; __global__ void __launch_bounds__(NTHR, 2) mega_fwd(Args args) {
;     ...
;         if (PHM(0) && (ph == 0 || ph == 2)) {
;             constexpr int I_SPLIT = NITEMS;
;             int hb = bid, nh = G, a0 = 0, a1 = 384, i0 = 0, i1 = I_SPLIT; bool work = true;
;             if (ph == 2) {
;                 const int last = (1600 + G - 1) / G, rem = 1600 - (last - 1) * G; const bool all = (rem == G);
;                 work = all || bid >= rem; hb = all ? bid : bid - rem; nh = all ? G : G - rem; a0 = 384; a1 = 768; i0 = I_SPLIT; i1 = NITEMS;
;             }
;             if (work) {
.LBB0_368:
	s_cmp_eq_u32 s48, 0
	s_mov_b64 s[8:9], -1
	s_movk_i32 s2, 0x180
	s_cselect_b64 s[6:7], -1, 0
	s_mov_b32 s16, s56
	s_mov_b32 s26, s3
	s_mov_b32 s5, s48
	s_mov_b32 s17, s48
	s_mov_b32 s101, 0x8e00
	s_andn2_b64 vcc, exec, s[6:7]
	s_cbranch_vccz .LBB0_371
	s_branch .LBB0_551

; __global__ void __launch_bounds__(NTHR, 2) mega_fwd(Args args) {
;     ...
;             if (ph == 2) {
;                 const int last = (1600 + G - 1) / G, rem = 1600 - (last - 1) * G; const bool all = (rem == G);
;                 work = all || bid >= rem; hb = all ? bid : bid - rem; nh = all ? G : G - rem; a0 = 384; a1 = 768; i0 = I_SPLIT; i1 = NITEMS;
.LBB0_370:
	v_readlane_b32 s8, v254, 32
	s_mov_b32 s17, 0x8e00
	s_mov_b32 s101, 0xbc00
	s_movk_i32 s2, 0x300
	s_movk_i32 s5, 0x180
	v_readlane_b32 s16, v254, 34
	v_readlane_b32 s26, v254, 35
	v_readlane_b32 s9, v254, 33
	s_andn2_b64 vcc, exec, s[6:7]
	s_cbranch_vccnz .LBB0_551

; __global__ void __launch_bounds__(NTHR, 2) mega_fwd(Args args) {
;     ...
;                     int it = i0 + hb * NWAVES + wave;
;                     if (it < i1) { P0_DECODE(it, aW, aK, aN, aWT, amode, ar); t_load(A, aW, aK, aN, ar, lane); }
.LBB0_393:
	s_ashr_i32 s20, s18, 6
	s_add_u32 s6, s82, 0x7a00000
	s_addc_u32 s7, s83, 0
	s_add_u32 s8, s82, 0x2200000
	s_addc_u32 s9, s83, 0
	s_lshl_b32 s2, s16, 3
	s_add_i32 s2, s2, s17
	s_add_i32 s5, s2, s20
	s_cmp_lt_i32 s5, s101
	v_and_b32_e32 v97, 63, v1
	s_cselect_b64 s[14:15], -1, 0
	s_cmp_ge_i32 s5, s101
	s_barrier
	s_cbranch_scc1 .LBB0_432
	s_cmpk_gt_i32 s5, 0x17ff
	s_mov_b64 s[16:17], -1
	s_cbranch_scc0 .LBB0_428
	s_cmpk_gt_u32 s5, 0x1fff
	s_cbranch_scc0 .LBB0_425
	s_cmpk_gt_u32 s5, 0x35ff
	s_cbranch_scc0 .LBB0_422
	s_cmpk_gt_u32 s5, 0x4bff
	s_cbranch_scc0 .LBB0_419
	s_cmpk_gt_u32 s5, 0x61ff
	s_cbranch_scc0 .LBB0_416
	s_cmpk_gt_u32 s5, 0x77ff
	s_cbranch_scc0 .LBB0_413
	s_cmpk_gt_u32 s5, 0x8dff
	s_cbranch_scc0 .LBB0_410
	s_cmpk_gt_u32 s5, 0xa3ff
	s_cbranch_scc0 .LBB0_407
	s_cmpk_gt_u32 s5, 0xb3ff
	s_cbranch_scc0 .LBB0_404
	s_load_dwordx2 s[10:11], s[0:1], 0x80
	s_add_i32 s40, s5, 0xffff4c00
	s_add_u32 s12, s82, 0xb600000
	s_addc_u32 s13, s83, 0
	s_mov_b64 s[16:17], 0

; __device__ __forceinline__ void t_load(float (&v)[32], const float* W, int K, int N, int item, int lane) {
;     const int nkb = K / 64, grp = item >> 3, w8 = item & 7, kb = 2 * (grp % (nkb / 2)) + (w8 & 1), nb = 4 * (grp / (nkb / 2)) + (w8 >> 1);
;     const float* p = W + (size_t)(64 * kb + (lane >> 5)) * N + 32 * nb + (lane & 31);
; #pragma unroll
;     for (int i = 0; i < 32; ++i) v[i] = p[(size_t)(2 * i) * N];
; }
; __global__ void __launch_bounds__(NTHR, 2) mega_fwd(Args args) {
;     ...
;                     if (it + hstep < i1) { P0_DECODE(it + hstep, bW, bK, bN, bWT, bmode, br); t_load(B, bW, bK, bN, br, lane); }
.LBB0_430:
	s_lshr_b32 s18, s38, 7
	v_cvt_f32_u32_e32 v1, s18
	s_sub_i32 s21, 0, s18
	s_ashr_i32 s17, s40, 3
	s_abs_i32 s19, s17
	v_rcp_iflag_f32_e32 v1, v1
	s_ashr_i32 s16, s40, 31
	v_lshlrev_b32_e32 v4, 2, v96
	v_mov_b32_e32 v5, v0
	v_mul_f32_e32 v1, 0x4f7ffffe, v1
	v_cvt_u32_f32_e32 v1, v1
	s_nop 0
	v_readfirstlane_b32 s22, v1
	s_mul_i32 s21, s21, s22
	s_mul_hi_u32 s21, s22, s21
	s_add_i32 s22, s22, s21
	s_mul_hi_u32 s21, s19, s22
	s_mul_i32 s22, s21, s18
	s_sub_i32 s19, s19, s22
	s_add_i32 s22, s21, 1
	s_sub_i32 s23, s19, s18
	s_cmp_ge_u32 s19, s18
	s_cselect_b32 s21, s22, s21
	s_cselect_b32 s19, s23, s19
	s_add_i32 s22, s21, 1
	s_cmp_ge_u32 s19, s18
	s_cselect_b32 s19, s22, s21
	s_xor_b32 s19, s19, s16
	s_sub_i32 s16, s19, s16
	s_mul_i32 s18, s16, s18
	s_sub_i32 s17, s17, s18
	s_lshl_b32 s18, s40, 6
	s_lshl_b32 s17, s17, 7
	s_and_b32 s18, s18, 64
	s_or_b32 s18, s17, s18
	v_lshrrev_b32_e32 v1, 5, v97
	v_or_b32_e32 v1, s18, v1
	s_ashr_i32 s17, s17, 31
	s_mul_i32 s17, s17, s2
	v_mad_u64_u32 v[2:3], s[18:19], v1, s2, 0
	v_add_u32_e32 v3, s17, v3
	s_waitcnt lgkmcnt(0)
	v_lshl_add_u64 v[2:3], v[2:3], 2, s[10:11]
	s_lshl_b32 s11, s40, 4
	s_lshl_b32 s10, s16, 7
	s_and_b32 s11, s11, 0x60
	s_or_b32 s10, s10, s11
	s_ashr_i32 s11, s10, 31
	v_lshl_add_u64 v[2:3], s[10:11], 2, v[2:3]
	v_lshl_add_u64 v[2:3], v[2:3], 0, v[4:5]
	s_lshl_b32 s90, s2, 1
	v_lshl_add_u64 v[4:5], s[90:91], 2, v[2:3]
	s_lshl_b32 s90, s2, 2
	global_load_dword v32, v[2:3], off nt
	global_load_dword v33, v[4:5], off nt
	v_lshl_add_u64 v[4:5], s[90:91], 2, v[2:3]
	s_mul_i32 s90, s2, 6
	global_load_dword v34, v[4:5], off nt
	v_lshl_add_u64 v[4:5], s[90:91], 2, v[2:3]
	s_lshl_b32 s90, s2, 3
	global_load_dword v35, v[4:5], off nt
	v_lshl_add_u64 v[4:5], s[90:91], 2, v[2:3]
	s_mul_i32 s90, s2, 10
	global_load_dword v36, v[4:5], off nt
	v_lshl_add_u64 v[4:5], s[90:91], 2, v[2:3]
	s_mul_i32 s90, s2, 12
	global_load_dword v37, v[4:5], off nt
	v_lshl_add_u64 v[4:5], s[90:91], 2, v[2:3]
	s_mul_i32 s90, s2, 14
	global_load_dword v38, v[4:5], off nt
	v_lshl_add_u64 v[4:5], s[90:91], 2, v[2:3]
	s_lshl_b32 s90, s2, 4
	global_load_dword v39, v[4:5], off nt
	v_lshl_add_u64 v[4:5], s[90:91], 2, v[2:3]
	s_mul_i32 s90, s2, 18
	global_load_dword v40, v[4:5], off nt
	v_lshl_add_u64 v[4:5], s[90:91], 2, v[2:3]
	s_mul_i32 s90, s2, 20
	global_load_dword v41, v[4:5], off nt
	v_lshl_add_u64 v[4:5], s[90:91], 2, v[2:3]
	s_mul_i32 s90, s2, 22
	global_load_dword v42, v[4:5], off nt
	v_lshl_add_u64 v[4:5], s[90:91], 2, v[2:3]
	s_mul_i32 s90, s2, 24
	global_load_dword v43, v[4:5], off nt
	v_lshl_add_u64 v[4:5], s[90:91], 2, v[2:3]
	s_mul_i32 s90, s2, 26
	global_load_dword v44, v[4:5], off nt
	v_lshl_add_u64 v[4:5], s[90:91], 2, v[2:3]
	s_mul_i32 s90, s2, 28
	global_load_dword v45, v[4:5], off nt
	v_lshl_add_u64 v[4:5], s[90:91], 2, v[2:3]
	s_mul_i32 s90, s2, 30
	global_load_dword v46, v[4:5], off nt
	v_lshl_add_u64 v[4:5], s[90:91], 2, v[2:3]
	s_lshl_b32 s90, s2, 5
	global_load_dword v47, v[4:5], off nt
	v_lshl_add_u64 v[4:5], s[90:91], 2, v[2:3]
	s_mul_i32 s90, s2, 34
	global_load_dword v48, v[4:5], off nt
	v_lshl_add_u64 v[4:5], s[90:91], 2, v[2:3]
	s_mul_i32 s90, s2, 36
	global_load_dword v49, v[4:5], off nt
	v_lshl_add_u64 v[4:5], s[90:91], 2, v[2:3]
	s_mul_i32 s90, s2, 38
	global_load_dword v50, v[4:5], off nt
	v_lshl_add_u64 v[4:5], s[90:91], 2, v[2:3]
	s_mul_i32 s90, s2, 40
	global_load_dword v51, v[4:5], off nt
	v_lshl_add_u64 v[4:5], s[90:91], 2, v[2:3]
	s_mul_i32 s90, s2, 42
	global_load_dword v52, v[4:5], off nt
	v_lshl_add_u64 v[4:5], s[90:91], 2, v[2:3]
	s_mul_i32 s90, s2, 44
	global_load_dword v53, v[4:5], off nt
	v_lshl_add_u64 v[4:5], s[90:91], 2, v[2:3]
	s_mul_i32 s90, s2, 46
	global_load_dword v54, v[4:5], off nt
	v_lshl_add_u64 v[4:5], s[90:91], 2, v[2:3]
	s_mul_i32 s90, s2, 48
	global_load_dword v55, v[4:5], off nt
	v_lshl_add_u64 v[4:5], s[90:91], 2, v[2:3]
	s_mul_i32 s90, s2, 50
	global_load_dword v56, v[4:5], off nt
	v_lshl_add_u64 v[4:5], s[90:91], 2, v[2:3]
	s_mul_i32 s90, s2, 52
	global_load_dword v57, v[4:5], off nt
	v_lshl_add_u64 v[4:5], s[90:91], 2, v[2:3]
	s_mul_i32 s90, s2, 54
	global_load_dword v58, v[4:5], off nt
	v_lshl_add_u64 v[4:5], s[90:91], 2, v[2:3]
	s_mul_i32 s90, s2, 56
	global_load_dword v59, v[4:5], off nt
	v_lshl_add_u64 v[4:5], s[90:91], 2, v[2:3]
	s_mul_i32 s90, s2, 58
	global_load_dword v60, v[4:5], off nt
	v_lshl_add_u64 v[4:5], s[90:91], 2, v[2:3]
	s_mul_i32 s90, s2, 60
	global_load_dword v61, v[4:5], off nt
	v_lshl_add_u64 v[4:5], s[90:91], 2, v[2:3]
	s_mul_i32 s90, s2, 62
	v_lshl_add_u64 v[2:3], s[90:91], 2, v[2:3]
	global_load_dword v62, v[4:5], off nt
	global_load_dword v63, v[2:3], off nt
	s_lshl_b32 s2, s26, 3
	s_add_i32 s22, s5, s2
	s_cmp_ge_i32 s22, s101
	s_cbranch_scc0 .LBB0_433

; __global__ void __launch_bounds__(NTHR, 2) mega_fwd(Args args) {
;     ...
;                     float A[32], B[32];
; #pragma unroll
;                     for (int i = 0; i < 32; ++i) { A[i] = 0.f; B[i] = 0.f; }
;                     const float* aW = nullptr; bf16* aWT = nullptr; int aK = 64, aN = 32, amode = 0, ar = 0;
;                     const float* bW = nullptr; bf16* bWT = nullptr; int bK = 64, bN = 32, bmode = 0, br = 0;
;                     int it = i0 + hb * NWAVES + wave;
;                     if (it < i1) { P0_DECODE(it, aW, aK, aN, aWT, amode, ar); t_load(A, aW, aK, aN, ar, lane); }
;                     if (it + hstep < i1) { P0_DECODE(it + hstep, bW, bK, bN, bWT, bmode, br); t_load(B, bW, bK, bN, br, lane); }
.LBB0_432:
	v_mov_b32_e32 v30, v0
	v_mov_b32_e32 v31, v0
	v_mov_b32_e32 v1, v0
	v_mov_b32_e32 v2, v0
	v_mov_b32_e32 v3, v0
	v_mov_b32_e32 v4, v0
	v_mov_b32_e32 v5, v0
	v_mov_b32_e32 v6, v0
	v_mov_b32_e32 v7, v0
	v_mov_b32_e32 v8, v0
	v_mov_b32_e32 v9, v0
	v_mov_b32_e32 v10, v0
	v_mov_b32_e32 v11, v0
	v_mov_b32_e32 v12, v0
	v_mov_b32_e32 v13, v0
	v_mov_b32_e32 v14, v0
	v_mov_b32_e32 v15, v0
	v_mov_b32_e32 v16, v0
	v_mov_b32_e32 v17, v0
	v_mov_b32_e32 v18, v0
	v_mov_b32_e32 v19, v0
	v_mov_b32_e32 v20, v0
	v_mov_b32_e32 v21, v0
	v_mov_b32_e32 v22, v0
	v_mov_b32_e32 v23, v0
	v_mov_b32_e32 v24, v0
	v_mov_b32_e32 v25, v0
	v_mov_b32_e32 v26, v0
	v_mov_b32_e32 v27, v0
	v_mov_b32_e32 v28, v0
	v_mov_b32_e32 v29, v0
	v_mov_b64_e32 v[62:63], v[30:31]
	s_mov_b64 s[12:13], 0
	s_mov_b32 s38, 64
	s_mov_b32 s40, 0
	s_mov_b32 s43, 0
	v_mov_b64_e32 v[60:61], v[28:29]
	v_mov_b64_e32 v[58:59], v[26:27]
	v_mov_b64_e32 v[56:57], v[24:25]
	v_mov_b64_e32 v[54:55], v[22:23]
	v_mov_b64_e32 v[52:53], v[20:21]
	v_mov_b64_e32 v[50:51], v[18:19]
	v_mov_b64_e32 v[48:49], v[16:17]
	v_mov_b64_e32 v[46:47], v[14:15]
	v_mov_b64_e32 v[44:45], v[12:13]
	v_mov_b64_e32 v[42:43], v[10:11]
	v_mov_b64_e32 v[40:41], v[8:9]
	v_mov_b64_e32 v[38:39], v[6:7]
	v_mov_b64_e32 v[36:37], v[4:5]
	v_mov_b64_e32 v[34:35], v[2:3]
	v_mov_b64_e32 v[32:33], v[0:1]
	s_lshl_b32 s2, s26, 3
	s_add_i32 s22, s5, s2
	s_cmp_ge_i32 s22, s101
	s_cbranch_scc1 .LBB0_431

; #define LAS __attribute__((address_space(3)))
; __device__ __forceinline__ void t_lds_write(const float (&v)[32], LAS float* scr, int lane) {
; #pragma unroll
;     for (int i = 0; i < 32; ++i) scr[(2 * i + (lane >> 5)) * 33 + (lane & 31)] = v[i];
;     asm volatile("s_waitcnt lgkmcnt(0)" ::: "memory");
; __global__ void __launch_bounds__(NTHR, 2) mega_fwd(Args args) {
;     ...
;                         { t_lds_write(A, scr, lane);
;                           const int eK = aK, eN = aN, emode = amode, er = ar; bf16* eWT = aWT;
;                           if (it + 2 * hstep < i1) { P0_DECODE(it + 2 * hstep, aW, aK, aN, aWT, amode, ar); t_load(A, aW, aK, aN, ar, lane); }
.LBB0_474:
	v_add_u32_e32 v12, 0x400, v11
	v_add_u32_e32 v13, 0x800, v11
	v_add_u32_e32 v14, 0xc00, v11
	v_add_u32_e32 v15, 0x1000, v11
	v_add_u32_e32 v16, 0x1400, v11
	v_add_u32_e32 v17, 0x1800, v11
	v_add_u32_e32 v18, 0x1c00, v11
	s_waitcnt vmcnt(30)
	ds_write2_b32 v11, v32, v33 offset1:66
	s_waitcnt vmcnt(28)
	ds_write2_b32 v11, v34, v35 offset0:132 offset1:198
	s_waitcnt vmcnt(26)
	ds_write2_b32 v12, v36, v37 offset0:8 offset1:74
	s_waitcnt vmcnt(24)
	ds_write2_b32 v12, v38, v39 offset0:140 offset1:206
	s_waitcnt vmcnt(22)
	ds_write2_b32 v13, v40, v41 offset0:16 offset1:82
	s_waitcnt vmcnt(20)
	ds_write2_b32 v13, v42, v43 offset0:148 offset1:214
	s_waitcnt vmcnt(18)
	ds_write2_b32 v14, v44, v45 offset0:24 offset1:90
	s_waitcnt vmcnt(16)
	ds_write2_b32 v14, v46, v47 offset0:156 offset1:222
	s_waitcnt vmcnt(14)
	ds_write2_b32 v15, v48, v49 offset0:32 offset1:98
	s_waitcnt vmcnt(12)
	ds_write2_b32 v15, v50, v51 offset0:164 offset1:230
	s_waitcnt vmcnt(10)
	ds_write2_b32 v16, v52, v53 offset0:40 offset1:106
	s_waitcnt vmcnt(8)
	ds_write2_b32 v16, v54, v55 offset0:172 offset1:238
	s_waitcnt vmcnt(6)
	ds_write2_b32 v17, v56, v57 offset0:48 offset1:114
	s_waitcnt vmcnt(4)
	ds_write2_b32 v17, v58, v59 offset0:180 offset1:246
	s_waitcnt vmcnt(2)
	ds_write2_b32 v18, v60, v61 offset0:56 offset1:122
	s_waitcnt vmcnt(0)
	ds_write2_b32 v18, v62, v63 offset0:188 offset1:254
	s_add_i32 s44, s5, s41
	s_waitcnt lgkmcnt(0)
	s_cmp_ge_i32 s44, s101
	s_cselect_b64 s[26:27], -1, 0
	s_and_b64 vcc, exec, s[26:27]
	s_cbranch_vccnz .LBB0_512
	s_cmpk_gt_i32 s44, 0x17ff
	s_mov_b64 s[34:35], -1
	s_cbranch_scc0 .LBB0_509
	s_cmpk_gt_u32 s44, 0x1fff
	s_cbranch_scc0 .LBB0_506
	s_cmpk_gt_u32 s44, 0x35ff
	s_cbranch_scc0 .LBB0_503
	s_cmpk_gt_u32 s44, 0x4bff
	s_cbranch_scc0 .LBB0_500
	s_cmpk_gt_u32 s44, 0x61ff
	s_cbranch_scc0 .LBB0_497
	s_cmpk_gt_u32 s44, 0x77ff
	s_cbranch_scc0 .LBB0_494
	s_cmpk_gt_u32 s44, 0x8dff
	s_cbranch_scc0 .LBB0_491
	s_cmpk_gt_u32 s44, 0xa3ff
	s_cbranch_scc0 .LBB0_488
	s_cmpk_gt_u32 s44, 0xb3ff
	s_mov_b64 s[28:29], -1
	s_cbranch_scc0 .LBB0_485
	s_load_dwordx2 s[30:31], s[0:1], 0x80
	s_add_i32 s45, s44, 0xffff4c00
	s_mov_b64 s[28:29], 0

; #define LAS __attribute__((address_space(3)))
; __device__ __forceinline__ unsigned pkbf(float lo, float hi) { return pg8::cvt_pk_bf16(lo, hi); }
; __device__ __forceinline__ void t_emit(int K, int N, bf16* WT, int mode, LAS float* scr, int item, int lane) {
;     const int nkb = K / 64, grp = item >> 3, w8 = item & 7, kb = 2 * (grp % (nkb / 2)) + (w8 & 1), nb = 4 * (grp / (nkb / 2)) + (w8 >> 1), k0 = 64 * kb, n0 = 32 * nb;
;     int drow0 = n0; if (mode) drow0 = 256 * (n0 >> 7) + (n0 & 127) + (mode == 2 ? 128 : 0);
;     const int c = lane & 7;
; #pragma unroll
;     for (int j = 0; j < 4; ++j) { const int n = (lane >> 3) + 8 * j; const LAS float* s = scr + (8 * c) * 33 + n;
;         v4u o; o.x = pkbf(s[0 * 33], s[1 * 33]); o.y = pkbf(s[2 * 33], s[3 * 33]); o.z = pkbf(s[4 * 33], s[5 * 33]); o.w = pkbf(s[6 * 33], s[7 * 33]);
;         *(v4u*)(WT + (size_t)(drow0 + n) * K + k0 + 8 * c) = o; }
;     asm volatile("s_waitcnt lgkmcnt(0)" ::: "memory");
; }
; __global__ void __launch_bounds__(NTHR, 2) mega_fwd(Args args) {
;     ...
;                           t_emit(eK, eN, eWT, emode, scr, er, lane); }
;                         if (it + hstep < i1) { t_lds_write(B, scr, lane);
;                           const int eK = bK, eN = bN, emode = bmode, er = br; bf16* eWT = bWT;
;                           if (it + 3 * hstep < i1) { P0_DECODE(it + 3 * hstep, bW, bK, bN, bWT, bmode, br); t_load(B, bW, bK, bN, br, lane); }
.LBB0_512:
	s_lshr_b32 s31, s38, 7
	v_cvt_f32_u32_e32 v3, s31
	s_sub_i32 s51, 0, s31
	s_ashr_i32 s30, s40, 3
	s_abs_i32 s35, s30
	v_rcp_iflag_f32_e32 v3, v3
	s_ashr_i32 s34, s40, 31
	ds_read2_b32 v[20:21], v7 offset1:33
	s_waitcnt lgkmcnt(0)
	v_cvt_pk_bf16_f32 v20, v20, v21
	v_mul_f32_e32 v3, 0x4f7ffffe, v3
	v_cvt_u32_f32_e32 v3, v3
	ds_read2_b32 v[22:23], v7 offset0:66 offset1:99
	s_waitcnt lgkmcnt(0)
	v_cvt_pk_bf16_f32 v21, v22, v23
	ds_read2_b32 v[22:23], v7 offset0:132 offset1:165
	v_readfirstlane_b32 s52, v3
	s_mul_i32 s51, s51, s52
	s_mul_hi_u32 s51, s52, s51
	s_add_i32 s52, s52, s51
	s_mul_hi_u32 s51, s35, s52
	s_mul_i32 s52, s51, s31
	s_sub_i32 s35, s35, s52
	s_add_i32 s52, s51, 1
	s_sub_i32 s54, s35, s31
	s_cmp_ge_u32 s35, s31
	s_cselect_b32 s51, s52, s51
	s_cselect_b32 s35, s54, s35
	s_add_i32 s52, s51, 1
	s_cmp_ge_u32 s35, s31
	s_cselect_b32 s35, s52, s51
	s_xor_b32 s35, s35, s34
	s_sub_i32 s35, s35, s34
	s_mul_i32 s31, s35, s31
	s_sub_i32 s30, s30, s31
	s_lshl_b32 s31, s40, 6
	s_lshl_b32 s30, s30, 7
	s_and_b32 s31, s31, 64
	s_or_b32 s34, s30, s31
	s_lshl_b32 s31, s40, 4
	s_lshl_b32 s30, s35, 7
	s_and_b32 s40, s31, 0x60
	s_lshl_b32 s31, s35, 8
	s_cmp_eq_u32 s43, 2
	s_cselect_b32 s35, 0x80, 0
	s_or_b32 s31, s31, s35
	s_cmp_eq_u32 s43, 0
	s_cselect_b32 s31, s30, s31
	s_ashr_i32 s35, s34, 31
	s_or_b32 s30, s31, s40
	s_lshl_b64 s[34:35], s[34:35], 1
	s_add_u32 s12, s12, s34
	s_addc_u32 s13, s13, s35
	v_mov_b32_e32 v3, v0
	v_lshl_add_u64 v[4:5], s[12:13], 0, v[2:3]
	s_waitcnt lgkmcnt(0)
	v_cvt_pk_bf16_f32 v22, v22, v23
	ds_read2_b32 v[24:25], v7 offset0:198 offset1:231
	v_or_b32_e32 v3, s30, v6
	s_waitcnt lgkmcnt(0)
	v_cvt_pk_bf16_f32 v23, v24, v25
	v_mad_u64_u32 v[24:25], s[12:13], v3, s38, 0
	s_ashr_i32 s12, s31, 31
	s_mul_i32 s31, s12, s38
	v_add_u32_e32 v25, s31, v25
	v_lshl_add_u64 v[24:25], v[24:25], 1, v[4:5]
	global_store_dwordx4 v[24:25], v[20:23], off
	ds_read2_b32 v[20:21], v7 offset0:8 offset1:41
	v_or_b32_e32 v3, s30, v8
	s_waitcnt lgkmcnt(0)
	v_cvt_pk_bf16_f32 v20, v20, v21
	ds_read2_b32 v[22:23], v7 offset0:74 offset1:107
	s_waitcnt lgkmcnt(0)
	v_cvt_pk_bf16_f32 v21, v22, v23
	ds_read2_b32 v[22:23], v7 offset0:140 offset1:173
	s_waitcnt lgkmcnt(0)
	v_cvt_pk_bf16_f32 v22, v22, v23
	ds_read2_b32 v[24:25], v7 offset0:206 offset1:239
	s_waitcnt lgkmcnt(0)
	v_cvt_pk_bf16_f32 v23, v24, v25
	v_mad_u64_u32 v[24:25], s[12:13], v3, s38, 0
	v_add_u32_e32 v25, s31, v25
	v_lshl_add_u64 v[24:25], v[24:25], 1, v[4:5]
	global_store_dwordx4 v[24:25], v[20:23], off
	ds_read2_b32 v[20:21], v7 offset0:16 offset1:49
	v_or_b32_e32 v3, s30, v9
	s_waitcnt lgkmcnt(0)
	v_cvt_pk_bf16_f32 v20, v20, v21
	ds_read2_b32 v[22:23], v7 offset0:82 offset1:115
	s_waitcnt lgkmcnt(0)
	v_cvt_pk_bf16_f32 v21, v22, v23
	ds_read2_b32 v[22:23], v7 offset0:148 offset1:181
	s_waitcnt lgkmcnt(0)
	v_cvt_pk_bf16_f32 v22, v22, v23
	ds_read2_b32 v[24:25], v7 offset0:214 offset1:247
	s_waitcnt lgkmcnt(0)
	v_cvt_pk_bf16_f32 v23, v24, v25
	v_mad_u64_u32 v[24:25], s[12:13], v3, s38, 0
	v_add_u32_e32 v25, s31, v25
	v_lshl_add_u64 v[24:25], v[24:25], 1, v[4:5]
	global_store_dwordx4 v[24:25], v[20:23], off
	ds_read2_b32 v[20:21], v7 offset0:24 offset1:57
	v_or_b32_e32 v3, s30, v10
	s_waitcnt lgkmcnt(0)
	v_cvt_pk_bf16_f32 v20, v20, v21
	ds_read2_b32 v[22:23], v7 offset0:90 offset1:123
	s_waitcnt lgkmcnt(0)
	v_cvt_pk_bf16_f32 v21, v22, v23
	ds_read2_b32 v[22:23], v7 offset0:156 offset1:189
	s_waitcnt lgkmcnt(0)
	v_cvt_pk_bf16_f32 v22, v22, v23
	ds_read2_b32 v[24:25], v7 offset0:222 offset1:255
	s_waitcnt lgkmcnt(0)
	v_cvt_pk_bf16_f32 v23, v24, v25
	v_mad_u64_u32 v[24:25], s[12:13], v3, s38, 0
	v_add_u32_e32 v25, s31, v25
	v_lshl_add_u64 v[4:5], v[24:25], 1, v[4:5]
	global_store_dwordx4 v[4:5], v[20:23], off
	s_waitcnt lgkmcnt(0)
	s_add_i32 s52, s5, s2
	s_cmp_ge_i32 s52, s101
	s_cbranch_scc1 .LBB0_473
	ds_write2_b32 v11, v64, v65 offset1:66
	ds_write2_b32 v11, v66, v67 offset0:132 offset1:198
	ds_write2_b32 v12, v68, v69 offset0:8 offset1:74
	ds_write2_b32 v12, v70, v71 offset0:140 offset1:206
	ds_write2_b32 v13, v72, v73 offset0:16 offset1:82
	ds_write2_b32 v13, v74, v75 offset0:148 offset1:214
	ds_write2_b32 v14, v76, v77 offset0:24 offset1:90
	ds_write2_b32 v14, v78, v79 offset0:156 offset1:222
	ds_write2_b32 v15, v80, v81 offset0:32 offset1:98
	ds_write2_b32 v15, v82, v83 offset0:164 offset1:230
	ds_write2_b32 v16, v84, v85 offset0:40 offset1:106
	ds_write2_b32 v16, v86, v87 offset0:172 offset1:238
	ds_write2_b32 v17, v88, v89 offset0:48 offset1:114
	ds_write2_b32 v17, v90, v91 offset0:180 offset1:246
	ds_write2_b32 v18, v92, v93 offset0:56 offset1:122
	ds_write2_b32 v18, v94, v95 offset0:188 offset1:254
	s_waitcnt lgkmcnt(0)
	s_add_i32 s51, s42, s5
	s_cmp_ge_i32 s51, s101
	s_mov_b32 s5, s37
	s_mov_b32 s40, s39
	s_mov_b32 s38, s36
	s_mov_b64 s[12:13], s[10:11]
	s_cbranch_scc1 .LBB0_472
	s_cmpk_gt_i32 s51, 0x17ff
	s_mov_b64 s[34:35], -1
	s_cbranch_scc0 .LBB0_548
	s_add_i32 s52, s52, s41
	s_cmpk_gt_u32 s51, 0x1fff
	s_cbranch_scc0 .LBB0_545
	s_cmpk_gt_u32 s51, 0x35ff
	s_cbranch_scc0 .LBB0_542
	s_cmpk_gt_u32 s51, 0x4bff
	s_cbranch_scc0 .LBB0_539
	s_cmpk_gt_u32 s51, 0x61ff
	s_cbranch_scc0 .LBB0_536
	s_cmpk_gt_u32 s51, 0x77ff
	s_cbranch_scc0 .LBB0_533
	s_cmpk_gt_u32 s51, 0x8dff
	s_cbranch_scc0 .LBB0_530
	s_cmpk_gt_u32 s51, 0xa3ff
	s_cbranch_scc0 .LBB0_527
	s_cmpk_gt_u32 s51, 0xb3ff
	s_mov_b64 s[12:13], -1
	s_cbranch_scc0 .LBB0_524
	s_load_dwordx2 s[30:31], s[0:1], 0x80
	s_add_i32 s5, s52, 0xffff4c00
	s_mov_b64 s[12:13], 0
